# attention unit: window branch first K/V tile loads hoisted to the selected-sweep exit (overlap with stash update)
# baseline (speedup 1.0000x reference)
.Lsel_exit:
	v_readlane_b32 s0, v255, 63
	v_readlane_b32 s1, v255, 56
	v_readlane_b32 s2, v255, 57
	v_readlane_b32 s3, v255, 62
	v_sub_u32_e64 v228, s20, 8 clamp
	v_ashrrev_i32_e32 v229, 2, v0
	s_lshl_b32 s0, s0, 1
	s_add_u32 s0, s1, s0
	s_addc_u32 s1, s2, 0
	s_add_u32 s2, s0, s3
	s_addc_u32 s3, s1, 0
	v_lshrrev_b32_e32 v228, 1, v228
	v_lshlrev_b32_e32 v228, 7, v228
	v_add_u32_e32 v228, v228, v229
	v_min_i32_e32 v228, 0x1fff, v228
	v_lshlrev_b32_e32 v230, 4, v0
	v_ashrrev_i32_e32 v229, 31, v228
	v_and_b32_e32 v230, 48, v230
	v_lshlrev_b64 v[228:229], 10, v[228:229]
	v_lshlrev_b32_e32 v230, 1, v230
	v_mov_b32_e32 v231, 0
	v_lshl_add_u64 v[228:229], s[2:3], 0, v[228:229]
	v_lshl_add_u64 v[228:229], v[228:229], 0, v[230:231]
	global_load_dwordx4 v[212:215], v[228:229], off offset:16
	global_load_dwordx4 v[216:219], v[228:229], off
	global_load_dwordx4 v[220:223], v[228:229], off offset:528
	global_load_dwordx4 v[224:227], v[228:229], off offset:512
	v_mov_b32_e32 v2, v252
	s_nop 1
	v_permlane32_swap_b32_e32 v252, v2
	v_mov_b32_e32 v5, v0
	v_add_f32_e32 v4, v252, v2
	v_mov_b32_e32 v2, 0
	v_readfirstlane_b32 s0, v5
	v_cmp_lt_f32_e32 vcc, 0, v4
	s_and_saveexec_b64 s[2:3], vcc
	v_readlane_b32 s48, v255, 60
	v_readlane_b32 s49, v255, 61
	v_readlane_b32 s23, v255, 41
	s_cbranch_execz .LBB0_1363
	s_add_i32 s1, s12, s21
	s_ashr_i32 s0, s0, 3
	v_lshrrev_b32_e32 v2, 2, v5
	s_and_b32 s0, s0, -8
	v_and_or_b32 v2, v2, 7, s1
	v_add_u32_e32 v2, s0, v2
	ds_read_b32 v2, v247 offset:4
	s_waitcnt lgkmcnt(0)
	v_div_scale_f32 v5, s[0:1], v4, v4, v2
	v_rcp_f32_e32 v6, v5
	v_div_scale_f32 v7, vcc, v2, v4, v2
	v_fma_f32 v8, -v5, v6, 1.0
	v_fmac_f32_e32 v6, v8, v6
	v_mul_f32_e32 v8, v7, v6
	v_fma_f32 v9, -v5, v8, v7
	v_fmac_f32_e32 v8, v9, v6
	v_fma_f32 v5, -v5, v8, v7
	v_div_fmas_f32 v5, v5, v6, v8
	v_div_fixup_f32 v2, v5, v4, v2
.LBB0_1363:
	s_or_b64 exec, exec, s[2:3]
	ds_read2st64_b32 v[4:5], v1 offset1:1
	v_mov_b32_e32 v8, v50
	v_mov_b32_e32 v9, v66
	v_mov_b32_e32 v66, v51
	v_readlane_b32 s0, v255, 63
	s_waitcnt lgkmcnt(0)
	v_lshlrev_b32_e32 v6, 16, v4
	v_and_b32_e32 v7, 0xffff0000, v4
	v_lshlrev_b32_e32 v4, 16, v5
	v_and_b32_e32 v5, 0xffff0000, v5
	v_pk_fma_f32 v[6:7], v[8:9], v[2:3], v[6:7] op_sel_hi:[1,0,1]
	v_pk_fma_f32 v[4:5], v[66:67], v[2:3], v[4:5] op_sel_hi:[1,0,1]
	v_cvt_pk_bf16_f32 v6, v6, v7
	v_cvt_pk_bf16_f32 v4, v4, v5
	ds_write2st64_b32 v1, v6, v4 offset1:1
	ds_read2st64_b32 v[4:5], v1 offset0:2 offset1:3
	v_mov_b32_e32 v8, v52
	v_mov_b32_e32 v9, v68
	v_mov_b32_e32 v68, v53
	s_lshl_b32 s0, s0, 1
	s_waitcnt lgkmcnt(0)
	v_lshlrev_b32_e32 v6, 16, v4
	v_and_b32_e32 v7, 0xffff0000, v4
	v_lshlrev_b32_e32 v4, 16, v5
	v_and_b32_e32 v5, 0xffff0000, v5
	v_pk_fma_f32 v[6:7], v[8:9], v[2:3], v[6:7] op_sel_hi:[1,0,1]
	v_pk_fma_f32 v[4:5], v[68:69], v[2:3], v[4:5] op_sel_hi:[1,0,1]
	v_cvt_pk_bf16_f32 v6, v6, v7
	v_cvt_pk_bf16_f32 v4, v4, v5
	ds_write2st64_b32 v1, v6, v4 offset0:2 offset1:3
	ds_read2st64_b32 v[4:5], v1 offset0:4 offset1:5
	v_mov_b32_e32 v8, v54
	v_mov_b32_e32 v9, v70
	v_mov_b32_e32 v70, v55
	v_readlane_b32 s1, v255, 56
	s_waitcnt lgkmcnt(0)
	v_lshlrev_b32_e32 v6, 16, v4
	v_and_b32_e32 v7, 0xffff0000, v4
	v_lshlrev_b32_e32 v4, 16, v5
	v_and_b32_e32 v5, 0xffff0000, v5
	v_pk_fma_f32 v[6:7], v[8:9], v[2:3], v[6:7] op_sel_hi:[1,0,1]
	v_pk_fma_f32 v[4:5], v[70:71], v[2:3], v[4:5] op_sel_hi:[1,0,1]
	v_cvt_pk_bf16_f32 v6, v6, v7
	v_cvt_pk_bf16_f32 v4, v4, v5
	ds_write2st64_b32 v1, v6, v4 offset0:4 offset1:5
	ds_read2st64_b32 v[4:5], v1 offset0:6 offset1:7
	v_mov_b32_e32 v8, v56
	v_mov_b32_e32 v9, v72
	v_mov_b32_e32 v72, v57
	s_add_u32 s0, s1, s0
	s_waitcnt lgkmcnt(0)
	v_lshlrev_b32_e32 v6, 16, v4
	v_and_b32_e32 v7, 0xffff0000, v4
	v_lshlrev_b32_e32 v4, 16, v5
	v_and_b32_e32 v5, 0xffff0000, v5
	v_pk_fma_f32 v[6:7], v[8:9], v[2:3], v[6:7] op_sel_hi:[1,0,1]
	v_pk_fma_f32 v[4:5], v[72:73], v[2:3], v[4:5] op_sel_hi:[1,0,1]
	v_cvt_pk_bf16_f32 v6, v6, v7
	v_cvt_pk_bf16_f32 v4, v4, v5
	ds_write2st64_b32 v1, v6, v4 offset0:6 offset1:7
	ds_read2st64_b32 v[4:5], v1 offset0:8 offset1:9
	v_mov_b32_e32 v8, v58
	v_mov_b32_e32 v9, v74
	v_mov_b32_e32 v74, v59
	v_readlane_b32 s1, v255, 57
	s_waitcnt lgkmcnt(0)
	v_lshlrev_b32_e32 v6, 16, v4
	v_and_b32_e32 v7, 0xffff0000, v4
	v_lshlrev_b32_e32 v4, 16, v5
	v_and_b32_e32 v5, 0xffff0000, v5
	v_pk_fma_f32 v[6:7], v[8:9], v[2:3], v[6:7] op_sel_hi:[1,0,1]
	v_pk_fma_f32 v[4:5], v[74:75], v[2:3], v[4:5] op_sel_hi:[1,0,1]
	v_cvt_pk_bf16_f32 v6, v6, v7
	v_cvt_pk_bf16_f32 v4, v4, v5
	ds_write2st64_b32 v1, v6, v4 offset0:8 offset1:9
	ds_read2st64_b32 v[4:5], v1 offset0:10 offset1:11
	v_mov_b32_e32 v8, v60
	v_mov_b32_e32 v9, v76
	v_mov_b32_e32 v76, v61
	s_addc_u32 s1, s1, 0
	s_waitcnt lgkmcnt(0)
	v_lshlrev_b32_e32 v6, 16, v4
	v_and_b32_e32 v7, 0xffff0000, v4
	v_lshlrev_b32_e32 v4, 16, v5
	v_and_b32_e32 v5, 0xffff0000, v5
	v_pk_fma_f32 v[6:7], v[8:9], v[2:3], v[6:7] op_sel_hi:[1,0,1]
	v_pk_fma_f32 v[4:5], v[76:77], v[2:3], v[4:5] op_sel_hi:[1,0,1]
	v_cvt_pk_bf16_f32 v6, v6, v7
	v_cvt_pk_bf16_f32 v4, v4, v5
	ds_write2st64_b32 v1, v6, v4 offset0:10 offset1:11
	ds_read2st64_b32 v[4:5], v1 offset0:12 offset1:13
	v_mov_b32_e32 v8, v62
	v_mov_b32_e32 v9, v78
	v_mov_b32_e32 v78, v63
	v_readlane_b32 s2, v255, 62
	s_waitcnt lgkmcnt(0)
	v_lshlrev_b32_e32 v6, 16, v4
	v_and_b32_e32 v7, 0xffff0000, v4
	v_lshlrev_b32_e32 v4, 16, v5
	v_and_b32_e32 v5, 0xffff0000, v5
	v_pk_fma_f32 v[6:7], v[8:9], v[2:3], v[6:7] op_sel_hi:[1,0,1]
	v_pk_fma_f32 v[4:5], v[78:79], v[2:3], v[4:5] op_sel_hi:[1,0,1]
	v_cvt_pk_bf16_f32 v6, v6, v7
	v_cvt_pk_bf16_f32 v4, v4, v5
	ds_write2st64_b32 v1, v6, v4 offset0:12 offset1:13
	ds_read2st64_b32 v[4:5], v1 offset0:14 offset1:15
	v_mov_b32_e32 v8, v64
	v_mov_b32_e32 v9, v80
	v_mov_b32_e32 v80, v65
	v_mov_b32_e32 v113, v0
	s_waitcnt lgkmcnt(0)
	v_lshlrev_b32_e32 v6, 16, v4
	v_and_b32_e32 v7, 0xffff0000, v4
	v_lshlrev_b32_e32 v4, 16, v5
	v_and_b32_e32 v5, 0xffff0000, v5
	v_pk_fma_f32 v[6:7], v[8:9], v[2:3], v[6:7] op_sel_hi:[1,0,1]
	v_pk_fma_f32 v[4:5], v[80:81], v[2:3], v[4:5] op_sel_hi:[1,0,1]
	v_cvt_pk_bf16_f32 v6, v6, v7
	v_cvt_pk_bf16_f32 v2, v4, v5
	s_add_u32 s2, s0, s2
	ds_write2st64_b32 v1, v6, v2 offset0:14 offset1:15
	s_addc_u32 s3, s1, 0
	v_readfirstlane_b32 s0, v113
	s_ashr_i32 s0, s0, 3
	s_and_b32 s0, s0, -8
	s_add_i32 s0, s0, s21
	v_bfe_u32 v2, v113, 2, 3
	v_or_b32_e32 v112, s0, v2
	v_sub_u32_e64 v2, s20, 8 clamp
	v_ashrrev_i32_e32 v4, 2, v113
	v_readfirstlane_b32 s0, v2
	s_lshr_b32 s4, s0, 1
	s_lshl_b32 s8, s4, 7
	v_add_u32_e32 v2, s8, v4
	v_min_i32_e32 v6, 0x1fff, v2
	v_lshlrev_b32_e32 v2, 4, v113
	v_ashrrev_i32_e32 v7, 31, v6
	v_and_b32_e32 v2, 48, v2
	v_lshlrev_b64 v[6:7], 10, v[6:7]
	v_lshl_add_u64 v[6:7], s[2:3], 0, v[6:7]
	v_lshlrev_b32_e32 v2, 1, v2
	v_lshl_add_u64 v[6:7], v[6:7], 0, v[2:3]
	v_lshlrev_b32_e32 v5, 5, v113
	s_movk_i32 s97, 0x90
	v_and_b32_e32 v5, 0x60, v5
	v_mul_lo_u32 v6, v4, s97
	s_waitcnt vmcnt(6)
	v_bfe_u32 v135, v113, 5, 1
	s_sub_i32 s1, s17, s4
	v_add3_u32 v134, 0, v6, v5
	v_mad_u64_u32 v[136:137], s[6:7], v4, 48, v[134:135]
	s_cmp_lt_i32 s1, 0
	v_readlane_b32 s64, v255, 32
	v_mov_b64_e32 v[202:203], 0x100
	v_mov_b64_e32 v[250:251], 0xff
	s_waitcnt vmcnt(2)
	ds_write_b128 v134, v[216:219]
	ds_write_b128 v134, v[212:215] offset:16
	s_waitcnt vmcnt(0)
	ds_write_b128 v136, v[224:227] offset:36864
	ds_write_b128 v136, v[220:223] offset:36880
	s_waitcnt lgkmcnt(0)
	s_barrier
	s_cbranch_scc1 .LBB0_1399
	v_and_b32_e32 v5, 63, v113
	v_and_b32_e32 v6, 31, v113
	v_lshl_add_u64 v[138:139], s[2:3], 0, v[2:3]
	v_mul_u32_u24_e32 v137, 0x90, v6
	v_and_b32_e32 v2, 16, v113
	v_lshrrev_b32_e32 v6, 3, v113
	v_bfe_u32 v7, v113, 2, 2
	v_lshlrev_b32_e32 v5, 2, v5
	v_and_or_b32 v6, v6, 4, v7
	v_and_or_b32 v2, v5, 12, v2
	v_mov_b32_e32 v16, v3
	v_mov_b32_e32 v17, v3
	v_mul_u32_u24_e32 v173, 0xc0, v6
	v_lshlrev_b32_e32 v174, 1, v2
	v_add_u32_e32 v177, 0x80, v4
	v_mov_b32_e32 v2, v3
	v_mov_b32_e32 v4, v3
	v_mov_b32_e32 v5, v3
	v_mov_b32_e32 v6, v3
	v_mov_b32_e32 v7, v3
	v_mov_b32_e32 v8, v3
	v_mov_b32_e32 v9, v3
	v_mov_b32_e32 v10, v3
	v_mov_b32_e32 v11, v3
	v_mov_b32_e32 v12, v3
	v_mov_b32_e32 v13, v3
	v_mov_b32_e32 v14, v3
	v_mov_b32_e32 v15, v3
	v_mov_b64_e32 v[34:35], v[16:17]
	v_mov_b64_e32 v[32:33], v[14:15]
	v_mov_b64_e32 v[30:31], v[12:13]
	v_mov_b64_e32 v[28:29], v[10:11]
	v_mov_b64_e32 v[26:27], v[8:9]
	v_mov_b64_e32 v[24:25], v[6:7]
	v_mov_b64_e32 v[22:23], v[4:5]
	v_mov_b64_e32 v[20:21], v[2:3]
	v_mov_b64_e32 v[18:19], v[16:17]
	v_lshlrev_b32_e32 v172, 4, v135
	v_add_u32_e32 v175, 0xfffffe01, v112
	v_lshlrev_b32_e32 v176, 2, v135
	s_add_i32 s9, s1, 1
	s_lshl_b32 s10, s4, 1
	s_add_i32 s11, s0, -1
	s_mov_b32 s16, 0
	v_mov_b32_e32 v178, 0
	v_mov_b64_e32 v[16:17], v[14:15]
	v_mov_b64_e32 v[14:15], v[12:13]
	v_mov_b64_e32 v[12:13], v[10:11]
	v_mov_b64_e32 v[10:11], v[8:9]
	v_mov_b64_e32 v[8:9], v[6:7]
	v_mov_b64_e32 v[6:7], v[4:5]
	v_mov_b64_e32 v[4:5], v[2:3]
	v_mov_b32_e32 v179, 0
	s_branch .LBB0_1366
